# v17 + windowed-attention item prologues: second K/V tile loads issued together with the first tile's (into spare registers) instead of after its wait
# speedup vs baseline: 1.0233x; 1.0004x over previous
; #define LAS __attribute__((address_space(3)))
; template <int DQK, bool WIN>
; DI void attn_run(int wv, const bf16_t* Qrow0, int qs, const bf16_t* Kb, int ks, const bf16_t* Vb, int vs,
;                  int kt0, int kt1, int qpos0, int window, LAS unsigned char* lds, f32x16 (&o)[2], float& m_out, float& l_out) {
;     ...
;     u32x4 rk0, rk1 = (u32x4){0u, 0u, 0u, 0u}, rv;
;     u32x4 nk0, nk1 = (u32x4){0u, 0u, 0u, 0u}, nv;
;     { const size_t ko = (size_t)kt0 * 64 * ks, vo = (size_t)kt0 * 64 * vs;
;       rk0 = gld16(kg0 + ko); if (k2) rk1 = gld16(kg1 + ko); rv = gld16(vg + vo);
;       *(LAS u32x4*)(lds + kl0) = rk0; if (k2) *(LAS u32x4*)(lds + kl1) = rk1; *(LAS u32x4*)(lds + vl) = rv; }
;     if (kt0 + 1 < kt1) { const size_t ko = (size_t)(kt0 + 1) * 64 * ks, vo = (size_t)(kt0 + 1) * 64 * vs;
;       rk0 = gld16(kg0 + ko); if (k2) rk1 = gld16(kg1 + ko); rv = gld16(vg + vo); }
;     nk0 = rk0; nv = rv;
; DI void phase_attn(int wv, const Params& p, int layer, LAS unsigned char* lds) {
;     ...
;             const int i2 = it - nA - nB - nC;
;             const int b = i2 / 96, rem = i2 % 96, g = rem >> 5, rem2 = rem & 31, kvh = rem2 >> 4, qt = rem2 & 15;
;             const int Ls = 2048 >> (2 * g);
;             const int tp0 = 128 * qt, sb = tp0 & ~(Ls - 1), u0 = tp0 - sb;
;             const int qh = 2 * kvh + (wave >> 2), wq = 32 * (wave & 3); const size_t row0 = (size_t)b * T;
;             const bf16_t* Q = (const bf16_t*)(ws + w.QD) + (size_t)g * Mc * 256 + ((row0 + tp0 + wq) * 4 + qh) * 64;
;             const bf16_t* K = (const bf16_t*)(ws + w.KD) + (size_t)g * Mc * 128 + ((row0 + sb) * 2 + kvh) * 64;
;             const bf16_t* V = (const bf16_t*)(ws + w.VD) + (size_t)g * Mc * 128 + ((row0 + sb) * 2 + kvh) * 64;
;             int k0 = (u0 >> 6) - 1, k1 = (u0 >> 6) + 3; if (k0 < 0) k0 = 0; if (k1 > (Ls >> 6)) k1 = (Ls >> 6);
;             attn_run<64, true>(wv, Q, 256, K, 128, V, 128, k0, k1, u0 + wq, 64, lds, o, mr, lr);
.LBB0_1239:
	s_cmp_ge_i32 s81, s0
	s_mov_b64 s[4:5], -1
	s_cbranch_scc0 .LBB0_1260
	s_mul_i32 s4, s8, 0x60
	s_cmp_ge_i32 s81, s4
	s_mov_b64 s[4:5], -1
	s_cbranch_scc0 .LBB0_1265
	s_mul_i32 s4, s8, 0xffffffa0
	s_add_i32 s4, s81, s4
	s_mul_hi_i32 s5, s4, 0x2aaaaaab
	s_lshr_b32 s12, s5, 31
	s_ashr_i32 s5, s5, 4
	s_add_i32 s24, s5, s12
	s_mul_i32 s5, s24, 0x60
	s_sub_i32 s4, s4, s5
	s_ashr_i32 s26, s4, 5
	s_lshl_b32 s38, s26, 1
	s_bfe_u32 s14, s4, 0x10004
	s_lshr_b32 s5, 0x800, s38
	s_lshl_b32 s4, s4, 7
	s_ashr_i32 s27, s26, 31
	s_and_b32 s13, s4, 0x780
	s_sub_i32 s4, 0, s5
	s_mul_i32 s5, s10, s27
	s_mul_hi_u32 s16, s10, s26
	s_add_i32 s5, s16, s5
	s_mul_i32 s16, s11, s26
	s_and_b32 s12, s13, s4
	s_lshl_b32 s4, s14, 1
	s_ashr_i32 s25, s24, 31
	s_add_i32 s17, s5, s16
	s_mul_i32 s16, s10, s26
	s_sub_i32 s15, s13, s12
	s_add_i32 s4, s4, s44
	s_lshl_b64 s[28:29], s[24:25], 11
	s_lshl_b64 s[20:21], s[16:17], 8
	s_lshl_b64 s[18:19], s[16:17], 9
	v_readlane_b32 s1, v255, 29
	s_add_u32 s30, s1, s18
	v_readlane_b32 s1, v255, 30
	s_addc_u32 s31, s1, s19
	s_or_b32 s5, s13, s79
	s_or_b32 s18, s28, s5
	s_mov_b32 s19, s29
	s_ashr_i32 s5, s4, 31
	s_lshl_b64 s[22:23], s[18:19], 9
	s_add_u32 s34, s30, s22
	s_addc_u32 s35, s31, s23
	s_lshl_b64 s[30:31], s[4:5], 7
	s_add_u32 s34, s34, s30
	s_addc_u32 s35, s35, s31
	v_readlane_b32 s1, v255, 31
	s_add_u32 s30, s1, s20
	v_readlane_b32 s1, v255, 32
	s_addc_u32 s31, s1, s21
	s_or_b32 s28, s28, s12
	s_lshl_b64 s[28:29], s[28:29], 8
	s_lshl_b32 s36, s14, 7
	s_or_b32 s28, s28, s36
	s_add_u32 s36, s30, s28
	s_addc_u32 s37, s31, s29
	v_readlane_b32 s1, v255, 35
	s_add_u32 s30, s1, s20
	v_readlane_b32 s1, v255, 41
	s_addc_u32 s31, s1, s21
	s_add_u32 s28, s30, s28
	s_addc_u32 s29, s31, s29
	s_ashr_i32 s30, s15, 6
	s_add_i32 s31, s30, 3
	s_lshr_b32 s38, 32, s38
	s_min_i32 s31, s31, s38
	s_mov_b32 s38, s33
	v_mov_b32_e32 v0, v145
	s_max_i32 s30, s30, 1
	v_mbcnt_lo_u32_b32 v0, -1, v0
	v_mbcnt_hi_u32_b32 v41, -1, v0
	v_and_b32_e32 v40, 31, v41
	v_bfe_u32 v42, v41, 5, 1
	v_lshlrev_b32_e32 v144, 9, v40
	v_lshl_add_u64 v[0:1], s[34:35], 0, v[144:145]
	v_lshlrev_b32_e32 v144, 4, v42
	v_lshl_add_u64 v[0:1], v[0:1], 0, v[144:145]
	global_load_dwordx4 v[80:83], v[0:1], off
	global_load_dwordx4 v[84:87], v[0:1], off offset:32
	global_load_dwordx4 v[88:91], v[0:1], off offset:64
	global_load_dwordx4 v[92:95], v[0:1], off offset:96
	v_lshl_add_u32 v1, s38, 6, v41
	v_ashrrev_i32_e32 v0, 31, v1
	v_lshrrev_b32_e32 v0, 29, v0
	v_add_u32_e32 v2, v1, v0
	v_ashrrev_i32_e32 v0, 3, v2
	v_and_b32_e32 v2, -8, v2
	v_sub_u32_e32 v2, v1, v2
	v_ashrrev_i32_e32 v4, 3, v1
	v_ashrrev_i32_e32 v1, 31, v0
	v_lshlrev_b64 v[32:33], 8, v[0:1]
	v_lshlrev_b32_e32 v34, 3, v2
	v_ashrrev_i32_e32 v5, 31, v4
	v_mul_lo_u32 v0, v0, s90
	s_add_i32 s68, s30, -1
	v_and_b32_e32 v3, 7, v41
	v_ashrrev_i32_e32 v35, 31, v34
	v_lshlrev_b64 v[36:37], 8, v[4:5]
	v_lshl_add_u32 v153, v2, 4, v0
	v_lshl_add_u64 v[0:1], s[36:37], 0, v[32:33]
	v_lshlrev_b32_e32 v38, 4, v3
	v_lshl_add_u64 v[2:3], s[28:29], 0, v[36:37]
	v_lshl_add_u64 v[0:1], v[34:35], 1, v[0:1]
	v_mov_b32_e32 v39, v145
	s_lshl_b64 s[28:29], s[68:69], 14
	v_lshl_add_u64 v[2:3], v[2:3], 0, v[38:39]
	v_lshl_add_u64 v[6:7], v[0:1], 0, s[28:29]
	global_load_dwordx4 v[96:99], v[6:7], off
	v_lshl_add_u64 v[6:7], v[2:3], 0, s[28:29]
	global_load_dwordx4 v[100:103], v[6:7], off
	v_mad_u64_u32 v[136:137], s[28:29], v4, s62, v[38:39]
	v_add_u32_e32 v5, 0, v153
	v_add_u32_e32 v4, 0, v136
	s_cmp_ge_i32 s30, s31
	s_cbranch_scc1 .Lpf_d_single
	s_lshl_b32 s68, s30, 14
	v_lshl_add_u64 v[0:1], v[0:1], 0, s[68:69]
	v_lshl_add_u64 v[2:3], v[2:3], 0, s[68:69]
	global_load_dwordx4 v[218:221], v[0:1], off
	global_load_dwordx4 v[222:225], v[2:3], off
	s_waitcnt vmcnt(2)
	ds_write_b128 v5, v[96:99]
	ds_write_b128 v4, v[100:103] offset:9216
	s_branch .LBB0_1243
.Lpf_d_single:
	s_waitcnt vmcnt(0)
	ds_write_b128 v5, v[96:99]
	ds_write_b128 v4, v[100:103] offset:9216
	v_mov_b32_e32 v218, v96
	v_mov_b32_e32 v219, v97
	v_mov_b32_e32 v220, v98
	v_mov_b32_e32 v221, v99
	v_mov_b32_e32 v222, v100
	v_mov_b32_e32 v223, v101
	v_mov_b32_e32 v224, v102
	v_mov_b32_e32 v225, v103
; #define LAS __attribute__((address_space(3)))
; #define ATTN_BAR() asm volatile("s_waitcnt lgkmcnt(0)\n\ts_barrier" ::: "memory")
; template <int DQK, bool WIN>
; DI void attn_run(int wv, const bf16_t* Qrow0, int qs, const bf16_t* Kb, int ks, const bf16_t* Vb, int vs,
;                  int kt0, int kt1, int qpos0, int window, LAS unsigned char* lds, f32x16 (&o)[2], float& m_out, float& l_out) {
;     ...
; #pragma unroll
;     for (int i = 0; i < 16; ++i) { o[0][i] = 0.f; o[1][i] = 0.f; }
;     float mrun = 0.f, lrun = 0.f; bool first = true;
;     f32x16 negm;
; #pragma unroll
;     for (int i = 0; i < 16; ++i) negm[i] = 0.f;
;     ...
;     u32x4 rk0, rk1 = (u32x4){0u, 0u, 0u, 0u}, rv;
;     u32x4 nk0, nk1 = (u32x4){0u, 0u, 0u, 0u}, nv;
;     { const size_t ko = (size_t)kt0 * 64 * ks, vo = (size_t)kt0 * 64 * vs;
;       rk0 = gld16(kg0 + ko); if (k2) rk1 = gld16(kg1 + ko); rv = gld16(vg + vo);
;       *(LAS u32x4*)(lds + kl0) = rk0; if (k2) *(LAS u32x4*)(lds + kl1) = rk1; *(LAS u32x4*)(lds + vl) = rv; }
;     if (kt0 + 1 < kt1) { const size_t ko = (size_t)(kt0 + 1) * 64 * ks, vo = (size_t)(kt0 + 1) * 64 * vs;
;       rk0 = gld16(kg0 + ko); if (k2) rk1 = gld16(kg1 + ko); rv = gld16(vg + vo); }
;     nk0 = rk0; nv = rv;
;     ATTN_BAR();
;     for (int kt = kt0; kt < kt1; ++kt) {
;         const int buf = (kt - kt0) & 1;
;         const bool more = (kt + 1 < kt1);
;         if (kt + 2 < kt1) { const size_t ko = (size_t)(kt + 2) * 64 * ks, vo = (size_t)(kt + 2) * 64 * vs;
;             nk0 = gld16(kg0 + ko); if (k2) nk1 = gld16(kg1 + ko); nv = gld16(vg + vo); }
;         bool need = true;
;         if (WIN) need = (64 * kt + 63 >= qpos0 - window) && (64 * kt <= qpos0 + 31 + window);
.LBB0_1243:
	s_waitcnt lgkmcnt(0)
	s_barrier
	v_mov_b32_e32 v15, 0
	s_cmp_gt_i32 s30, s31
	v_mov_b32_e32 v14, v15
	v_mov_b32_e32 v13, v15
	v_mov_b32_e32 v12, v15
	v_mov_b32_e32 v11, v15
	v_mov_b32_e32 v10, v15
	v_mov_b32_e32 v9, v15
	v_mov_b32_e32 v8, v15
	v_mov_b32_e32 v7, v15
	v_mov_b32_e32 v6, v15
	v_mov_b32_e32 v5, v15
	v_mov_b32_e32 v4, v15
	v_mov_b32_e32 v3, v15
	v_mov_b32_e32 v2, v15
	v_mov_b32_e32 v1, v15
	v_mov_b32_e32 v0, v15
	v_mov_b32_e32 v31, v15
	v_mov_b32_e32 v30, v15
	v_mov_b32_e32 v29, v15
	v_mov_b32_e32 v28, v15
	v_mov_b32_e32 v27, v15
	v_mov_b32_e32 v26, v15
	v_mov_b32_e32 v25, v15
	v_mov_b32_e32 v24, v15
	v_mov_b32_e32 v23, v15
	v_mov_b32_e32 v22, v15
	v_mov_b32_e32 v21, v15
	v_mov_b32_e32 v20, v15
	v_mov_b32_e32 v19, v15
	v_mov_b32_e32 v18, v15
	v_mov_b32_e32 v17, v15
	v_mov_b32_e32 v16, v15
	v_mov_b32_e32 v137, v15
	v_mov_b32_e32 v160, v15
	s_cbranch_scc1 .LBB0_1262
	v_lshrrev_b32_e32 v0, 2, v41
	v_lshlrev_b32_e32 v1, 2, v42
	v_readlane_b32 s1, v255, 51
	s_lshl_b32 s68, s14, 6
	v_and_or_b32 v0, v0, 3, v1
	s_add_i32 s14, s1, s12
	v_mul_u32_u24_e32 v156, 0xc0, v0
	v_add_u32_e32 v0, s14, v1
	s_or_b32 s35, s15, s79
	v_sub_u32_e32 v0, v0, v40
	v_readlane_b32 s1, v255, 52
	s_sub_i32 s34, s35, 64
	s_addk_i32 s35, 0x5f
	s_lshl_b32 s44, s30, 6
	v_subrev_u32_e32 v158, s13, v0
	s_add_i32 s13, s1, s13
	s_lshl_b64 s[14:15], s[26:27], 19
	v_add_u32_e32 v0, s13, v40
	s_add_u32 s13, s14, 0xc90000
	s_addc_u32 s26, s15, 0
	s_mul_i32 s26, s8, s26
	s_mul_hi_u32 s27, s8, s13
	s_add_i32 s26, s27, s26
	s_mul_i32 s27, s9, s13
	s_add_i32 s26, s26, s27
	s_mul_i32 s13, s8, s13
	v_readlane_b32 s1, v255, 53
	s_add_u32 s13, s1, s13
	v_readlane_b32 s29, v255, 54
	s_addc_u32 s27, s29, s26
	s_lshl_b32 s28, s30, 14
	s_add_u32 s26, s13, s28
	v_subrev_u32_e32 v0, s12, v0
	s_addc_u32 s27, s27, 0
	s_lshl_b64 s[24:25], s[24:25], 18
	s_lshl_b32 s12, s12, 7
	s_or_b32 s24, s24, s12
	s_or_b64 s[12:13], s[24:25], s[68:69]
	s_lshl_b64 s[12:13], s[12:13], 1
	s_add_u32 s14, s14, 0xb10000
	s_addc_u32 s15, s15, 0
	s_mul_i32 s15, s8, s15
	s_mul_hi_u32 s24, s8, s14
	s_add_i32 s15, s24, s15
	s_mul_i32 s24, s9, s14
	s_add_i32 s15, s15, s24
	s_mul_i32 s14, s8, s14
	s_add_u32 s14, s1, s14
	v_sub_u32_e32 v0, v0, v1
	s_addc_u32 s15, s29, s15
	v_subrev_u32_e32 v159, s44, v0
	v_lshl_add_u64 v[0:1], s[26:27], 0, v[36:37]
	v_mov_b32_e32 v39, v145
	s_add_u32 s14, s14, s28
	v_lshl_add_u64 v[0:1], v[0:1], 0, v[38:39]
	s_addc_u32 s15, s15, 0
	v_lshl_add_u64 v[138:139], v[0:1], 0, s[12:13]
	s_add_u32 s12, s12, s14
	s_addc_u32 s13, s13, s15
	v_lshlrev_b32_e32 v2, 1, v41
	v_lshlrev_b32_e32 v3, 3, v41
	v_lshl_add_u64 v[0:1], s[12:13], 0, v[32:33]
	v_mov_b32_e32 v137, 0
	s_waitcnt vmcnt(0)
	v_mov_b32_e32 v96, v218
	v_mov_b32_e32 v97, v219
	v_mov_b32_e32 v98, v220
	v_mov_b32_e32 v99, v221
	v_mov_b32_e32 v100, v222
	v_mov_b32_e32 v101, v223
	v_mov_b32_e32 v102, v224
	v_mov_b32_e32 v103, v225
	v_mov_b64_e32 v[106:107], v[102:103]
	v_mov_b64_e32 v[110:111], v[98:99]
	v_mul_u32_u24_e32 v154, 0x90, v40
	v_and_b32_e32 v155, 32, v2
	v_and_b32_e32 v157, 24, v3
	v_lshl_add_u64 v[140:141], v[34:35], 1, v[0:1]
	s_mov_b64 s[24:25], -1
	s_mov_b32 s12, 0
	s_mov_b32 s13, 0
	v_mov_b32_e32 v160, 0
	v_mov_b32_e32 v16, 0
	v_mov_b32_e32 v17, v137
	v_mov_b32_e32 v18, v137
	v_mov_b32_e32 v19, v137
	v_mov_b32_e32 v20, v137
	v_mov_b32_e32 v21, v137
	v_mov_b32_e32 v22, v137
	v_mov_b32_e32 v23, v137
	v_mov_b32_e32 v24, v137
	v_mov_b32_e32 v25, v137
	v_mov_b32_e32 v26, v137
	v_mov_b32_e32 v27, v137
	v_mov_b32_e32 v28, v137
	v_mov_b32_e32 v29, v137
	v_mov_b32_e32 v30, v137
	v_mov_b32_e32 v31, v137
	v_mov_b32_e32 v0, v137
	v_mov_b32_e32 v1, v137
	v_mov_b32_e32 v2, v137
	v_mov_b32_e32 v3, v137
	v_mov_b32_e32 v4, v137
	v_mov_b32_e32 v5, v137
	v_mov_b32_e32 v6, v137
	v_mov_b32_e32 v7, v137
	v_mov_b32_e32 v8, v137
	v_mov_b32_e32 v9, v137
	v_mov_b32_e32 v10, v137
	v_mov_b32_e32 v11, v137
	v_mov_b32_e32 v12, v137
	v_mov_b32_e32 v13, v137
	v_mov_b32_e32 v14, v137
	v_mov_b32_e32 v15, v137
	v_mov_b32_e32 v32, 0
	v_mov_b32_e32 v33, v137
	v_mov_b32_e32 v34, v137
	v_mov_b32_e32 v35, v137
	v_mov_b32_e32 v36, v137
	v_mov_b32_e32 v37, v137
	v_mov_b32_e32 v38, v137
	v_mov_b32_e32 v39, v137
	v_mov_b32_e32 v40, v137
	v_mov_b32_e32 v41, v137
	v_mov_b32_e32 v42, v137
	v_mov_b32_e32 v43, v137
	v_mov_b32_e32 v44, v137
	v_mov_b32_e32 v45, v137
	v_mov_b32_e32 v46, v137
	v_mov_b32_e32 v47, v137
	v_mov_b64_e32 v[104:105], v[100:101]
	v_mov_b64_e32 v[108:109], v[96:97]
	s_add_i32 s14, s30, s12
	s_add_i32 s15, s14, 1
	s_cmp_ge_i32 s15, s31
	s_cbranch_scc1 .LBB0_1246

; #define LAS __attribute__((address_space(3)))
; template <int DQK, bool WIN>
; DI void attn_run(int wv, const bf16_t* Qrow0, int qs, const bf16_t* Kb, int ks, const bf16_t* Vb, int vs,
;                  int kt0, int kt1, int qpos0, int window, LAS unsigned char* lds, f32x16 (&o)[2], float& m_out, float& l_out) {
;     ...
;     u32x4 rk0, rk1 = (u32x4){0u, 0u, 0u, 0u}, rv;
;     u32x4 nk0, nk1 = (u32x4){0u, 0u, 0u, 0u}, nv;
;     { const size_t ko = (size_t)kt0 * 64 * ks, vo = (size_t)kt0 * 64 * vs;
;       rk0 = gld16(kg0 + ko); if (k2) rk1 = gld16(kg1 + ko); rv = gld16(vg + vo);
;       *(LAS u32x4*)(lds + kl0) = rk0; if (k2) *(LAS u32x4*)(lds + kl1) = rk1; *(LAS u32x4*)(lds + vl) = rv; }
;     if (kt0 + 1 < kt1) { const size_t ko = (size_t)(kt0 + 1) * 64 * ks, vo = (size_t)(kt0 + 1) * 64 * vs;
;       rk0 = gld16(kg0 + ko); if (k2) rk1 = gld16(kg1 + ko); rv = gld16(vg + vo); }
;     nk0 = rk0; nv = rv;
; DI void phase_attn(int wv, const Params& p, int layer, LAS unsigned char* lds) {
;     ...
;         } else if (it < nA + nB + nC) {
;             const bool isC = it >= nA + nB;
;             const int i2 = it - nA - (isC ? nB : 0);
;             const int b = i2 >> 5, rem = i2 & 31, kvh = rem >> 4, qt = rem & 15;
;             const int qh = 2 * kvh + (wave >> 2), t0 = 128 * qt + 32 * (wave & 3); const size_t row0 = (size_t)b * T;
;             const bf16_t* Q = (const bf16_t*)(ws + (isC ? w.QC : w.QB)) + ((row0 + t0) * 4 + qh) * 64;
;             const bf16_t* K = (const bf16_t*)(ws + (isC ? w.KC : w.KB)) + (row0 * 2 + kvh) * 64;
;             const bf16_t* V = (const bf16_t*)(ws + (isC ? w.VC : w.VB)) + (row0 * 2 + kvh) * 64;
;             const size_t rw0 = row0 + t0;
;             if (!isC) {
;                 attn_run<64, false>(wv, Q, 256, K, 128, V, 128, 0, 32, 0, 0, lds, o, mr, lr);
;                 attn_store(o, __builtin_amdgcn_rcpf(lr), YG + (Mc + rw0) * 256 + qh * 64, 256, ZS + rw0 * 1024 + 256 + qh * 64, 1024, lane, stage);
;             } else {
;                 int k0 = 2 * qt - 2, k1 = 2 * qt + 4; if (k0 < 0) k0 = 0; if (k1 > 32) k1 = 32;
;                 attn_run<64, true>(wv, Q, 256, K, 128, V, 128, k0, k1, t0, 128, lds, o, mr, lr);
.LBB0_1265:
	s_and_b64 vcc, exec, s[4:5]
	s_cbranch_vccz .LBB0_1296
	s_bfe_u32 s4, s81, 0x10004
	s_lshl_b32 s34, s4, 7
	v_readlane_b32 s28, v255, 27
	s_cmp_lt_i32 s81, s28
	v_readlane_b32 s1, v255, 12
	s_cselect_b32 s13, s55, s1
	v_readlane_b32 s1, v255, 15
	s_cselect_b32 s86, s75, s1
	v_readlane_b32 s1, v255, 24
	s_cselect_b32 s76, s39, s1
	v_readlane_b32 s1, v255, 25
	s_cselect_b32 s5, 0, s0
	s_cselect_b32 s35, s42, s1
	v_readlane_b32 s1, v255, 26
	s_cselect_b32 s15, s54, s91
	s_cselect_b32 s63, s45, s1
	s_add_i32 s5, s0, s5
	s_sub_i32 s5, s81, s5
	s_ashr_i32 s18, s5, 5
	s_and_b32 s12, s81, 15
	s_lshl_b32 s4, s4, 1
	s_add_i32 s16, s4, s44
	s_lshl_b32 s4, s12, 7
	s_ashr_i32 s19, s18, 31
	s_or_b32 s14, s4, s79
	s_lshl_b64 s[4:5], s[18:19], 11
	s_add_u32 s15, s6, s15
	s_addc_u32 s13, s7, s13
	s_or_b32 s4, s4, s14
	s_ashr_i32 s17, s16, 31
	s_lshl_b64 s[26:27], s[4:5], 9
	s_add_u32 s15, s15, s26
	s_addc_u32 s13, s13, s27
	s_lshl_b64 s[20:21], s[16:17], 7
	s_add_u32 s24, s15, s20
	s_addc_u32 s25, s13, s21
	s_add_u32 s13, s6, s86
	s_addc_u32 s15, s7, s76
	s_lshl_b64 s[18:19], s[18:19], 19
	s_or_b32 s17, s18, s34
	s_add_u32 s20, s13, s17
	s_addc_u32 s21, s15, s19
	s_add_u32 s13, s6, s35
	s_addc_u32 s15, s7, s63
	s_add_u32 s22, s13, s17
	s_addc_u32 s23, s15, s19
	s_cmp_ge_i32 s81, s28
	s_mov_b64 s[28:29], -1
	s_cbranch_scc0 .LBB0_1288
	s_lshl_b32 s12, s12, 1
	v_sub_u32_e64 v4, s12, 2 clamp
	s_min_u32 s17, s12, 28
	s_mov_b32 s12, s33
	v_mov_b32_e32 v0, v145
	v_mov_b32_e32 v39, v145
	v_mbcnt_lo_u32_b32 v0, -1, v0
	v_mbcnt_hi_u32_b32 v41, -1, v0
	v_and_b32_e32 v40, 31, v41
	v_bfe_u32 v42, v41, 5, 1
	v_lshlrev_b32_e32 v144, 9, v40
	v_lshl_add_u64 v[0:1], s[24:25], 0, v[144:145]
	v_lshlrev_b32_e32 v144, 4, v42
	v_lshl_add_u64 v[0:1], v[0:1], 0, v[144:145]
	global_load_dwordx4 v[80:83], v[0:1], off
	global_load_dwordx4 v[84:87], v[0:1], off offset:32
	global_load_dwordx4 v[88:91], v[0:1], off offset:64
	global_load_dwordx4 v[92:95], v[0:1], off offset:96
	v_lshl_add_u32 v1, s12, 6, v41
	v_ashrrev_i32_e32 v0, 31, v1
	v_lshrrev_b32_e32 v0, 29, v0
	v_add_u32_e32 v2, v1, v0
	v_ashrrev_i32_e32 v0, 3, v2
	v_and_b32_e32 v2, -8, v2
	v_sub_u32_e32 v2, v1, v2
	v_ashrrev_i32_e32 v6, 3, v1
	v_ashrrev_i32_e32 v1, 31, v0
	v_lshlrev_b64 v[32:33], 8, v[0:1]
	v_lshlrev_b32_e32 v34, 3, v2
	v_ashrrev_i32_e32 v7, 31, v6
	v_mul_lo_u32 v0, v0, s90
	v_and_b32_e32 v3, 7, v41
	v_ashrrev_i32_e32 v35, 31, v34
	v_lshlrev_b64 v[36:37], 8, v[6:7]
	v_lshl_add_u32 v153, v2, 4, v0
	v_lshl_add_u64 v[0:1], s[20:21], 0, v[32:33]
	v_lshlrev_b32_e32 v38, 4, v3
	v_lshl_add_u64 v[2:3], s[22:23], 0, v[36:37]
	v_lshl_add_u64 v[0:1], v[34:35], 1, v[0:1]
	v_lshlrev_b32_e32 v8, 14, v4
	v_mov_b32_e32 v9, v145
	v_lshl_add_u64 v[2:3], v[2:3], 0, v[38:39]
	v_lshl_add_u64 v[10:11], v[0:1], 0, v[8:9]
	global_load_dwordx4 v[96:99], v[10:11], off
	v_lshl_add_u64 v[8:9], v[2:3], 0, v[8:9]
	global_load_dwordx4 v[100:103], v[8:9], off
	v_mad_u64_u32 v[136:137], s[12:13], v6, s62, v[38:39]
	v_readfirstlane_b32 s12, v4
	s_add_i32 s17, s17, 4
	v_add_u32_e32 v5, 0, v153
	s_or_b32 s12, s12, 1
	s_mov_b32 s1, s91
	s_cmp_ge_u32 s12, s17
	s_cbranch_scc1 .Lpf_c_single
	s_lshl_b32 s68, s12, 14
	v_lshl_add_u64 v[0:1], v[0:1], 0, s[68:69]
	v_lshl_add_u64 v[2:3], v[2:3], 0, s[68:69]
	global_load_dwordx4 v[218:221], v[0:1], off
	global_load_dwordx4 v[222:225], v[2:3], off
	s_waitcnt vmcnt(2)
	ds_write_b128 v5, v[96:99]
	v_add_u32_e32 v5, 0, v136
	ds_write_b128 v5, v[100:103] offset:9216
	s_branch .LBB0_1269
.Lpf_c_single:
	s_waitcnt vmcnt(0)
	ds_write_b128 v5, v[96:99]
	v_add_u32_e32 v5, 0, v136
	ds_write_b128 v5, v[100:103] offset:9216
	v_mov_b32_e32 v218, v96
	v_mov_b32_e32 v219, v97
	v_mov_b32_e32 v220, v98
	v_mov_b32_e32 v221, v99
	v_mov_b32_e32 v222, v100
	v_mov_b32_e32 v223, v101
	v_mov_b32_e32 v224, v102
	v_mov_b32_e32 v225, v103
; #define LAS __attribute__((address_space(3)))
; #define ATTN_BAR() asm volatile("s_waitcnt lgkmcnt(0)\n\ts_barrier" ::: "memory")
; template <int DQK, bool WIN>
; DI void attn_run(int wv, const bf16_t* Qrow0, int qs, const bf16_t* Kb, int ks, const bf16_t* Vb, int vs,
;                  int kt0, int kt1, int qpos0, int window, LAS unsigned char* lds, f32x16 (&o)[2], float& m_out, float& l_out) {
;     ...
;     const int kr0 = tid / CPR, kc0 = tid % CPR;
;     const int kr1 = (tid + 512) / CPR, kc1 = (tid + 512) % CPR;
;     const bool k2 = (DQK == 96) && (tid < 256);
;     const int vr = tid >> 3, vc = tid & 7;
;     const bf16_t* kg0 = Kb + (size_t)kr0 * ks + kc0 * 8;
;     const bf16_t* kg1 = Kb + (size_t)kr1 * ks + kc1 * 8;
;     const bf16_t* vg = Vb + (size_t)vr * vs + vc * 8;
;     const int kl0 = kr0 * KP + kc0 * 16, kl1 = kr1 * KP + kc1 * 16, vl = KBYTES + vr * VP + vc * 16;
;     const int kfo = r32 * KP + h * 16;
;     const int i16 = lane & 15, qq = i16 >> 2, pp = i16 & 3, blk = (lane >> 4) & 1;
;     const int vfo = KBYTES + (4 * h + qq) * VP + 32 * blk + 8 * pp;
; #pragma unroll
;     for (int i = 0; i < 16; ++i) { o[0][i] = 0.f; o[1][i] = 0.f; }
;     float mrun = 0.f, lrun = 0.f; bool first = true;
;     f32x16 negm;
; #pragma unroll
;     for (int i = 0; i < 16; ++i) negm[i] = 0.f;
;     ...
;     u32x4 rk0, rk1 = (u32x4){0u, 0u, 0u, 0u}, rv;
;     u32x4 nk0, nk1 = (u32x4){0u, 0u, 0u, 0u}, nv;
;     { const size_t ko = (size_t)kt0 * 64 * ks, vo = (size_t)kt0 * 64 * vs;
;       rk0 = gld16(kg0 + ko); if (k2) rk1 = gld16(kg1 + ko); rv = gld16(vg + vo);
;       *(LAS u32x4*)(lds + kl0) = rk0; if (k2) *(LAS u32x4*)(lds + kl1) = rk1; *(LAS u32x4*)(lds + vl) = rv; }
;     if (kt0 + 1 < kt1) { const size_t ko = (size_t)(kt0 + 1) * 64 * ks, vo = (size_t)(kt0 + 1) * 64 * vs;
;       rk0 = gld16(kg0 + ko); if (k2) rk1 = gld16(kg1 + ko); rv = gld16(vg + vo); }
;     nk0 = rk0; nv = rv;
;     ATTN_BAR();
.LBB0_1269:
	s_waitcnt lgkmcnt(0)
	s_barrier
	v_mov_b32_e32 v15, 0
	v_cmp_le_u32_e32 vcc, s17, v4
	s_mov_b32 s91, s39
	s_and_b64 vcc, exec, vcc
	v_mov_b32_e32 v14, v15
	v_mov_b32_e32 v13, v15
	v_mov_b32_e32 v12, v15
	v_mov_b32_e32 v11, v15
	v_mov_b32_e32 v10, v15
	v_mov_b32_e32 v9, v15
	v_mov_b32_e32 v8, v15
	v_mov_b32_e32 v7, v15
	v_mov_b32_e32 v6, v15
	v_mov_b32_e32 v5, v15
	v_mov_b32_e32 v4, v15
	v_mov_b32_e32 v3, v15
	v_mov_b32_e32 v2, v15
	v_mov_b32_e32 v1, v15
	v_mov_b32_e32 v0, v15
	v_mov_b32_e32 v31, v15
	v_mov_b32_e32 v30, v15
	v_mov_b32_e32 v29, v15
	v_mov_b32_e32 v28, v15
	v_mov_b32_e32 v27, v15
	v_mov_b32_e32 v26, v15
	v_mov_b32_e32 v25, v15
	v_mov_b32_e32 v24, v15
	v_mov_b32_e32 v23, v15
	v_mov_b32_e32 v22, v15
	v_mov_b32_e32 v21, v15
	v_mov_b32_e32 v20, v15
	v_mov_b32_e32 v19, v15
	v_mov_b32_e32 v18, v15
	v_mov_b32_e32 v17, v15
	v_mov_b32_e32 v16, v15
	v_mov_b32_e32 v137, v15
	v_mov_b32_e32 v160, v15
	s_cbranch_vccnz .LBB0_1287
	s_and_b32 s13, s77, 15
	s_lshl_b32 s15, s13, 1
	s_min_u32 s28, s15, 2
	v_lshrrev_b32_e32 v0, 2, v41
	v_lshlrev_b32_e32 v1, 2, v42
	s_sub_i32 s15, s15, s28
	v_and_or_b32 v0, v0, 3, v1
	s_add_i32 s68, s15, 2
	v_readlane_b32 s15, v255, 51
	v_mul_u32_u24_e32 v156, 0xc0, v0
	s_lshl_b32 s30, s28, 6
	v_add_u32_e32 v0, s15, v1
	v_readlane_b32 s15, v255, 55
	s_mov_b32 s40, s75
	s_sub_i32 s12, 0, s30
	s_lshl_b32 s13, s13, 7
	s_lshl_b64 s[28:29], s[68:69], 14
	s_add_i32 s75, s14, 0xffffff80
	s_addk_i32 s14, 0x9f
	s_add_i32 s15, s15, s30
	v_sub_u32_e32 v158, v0, v40
	v_add_u32_e32 v0, s15, v40
	s_add_u32 s15, s6, s35
	s_addc_u32 s30, s7, s63
	s_add_u32 s15, s15, s18
	s_addc_u32 s30, s30, s19
	s_add_u32 s15, s15, s28
	s_addc_u32 s31, s30, s29
	s_add_u32 s30, s34, s15
	s_addc_u32 s31, 0, s31
	s_add_u32 s15, s6, s86
	v_sub_u32_e32 v159, v0, v1
	v_lshl_add_u64 v[0:1], s[30:31], 0, v[36:37]
	s_addc_u32 s30, s7, s76
	s_add_u32 s15, s15, s18
	s_addc_u32 s30, s30, s19
	s_add_u32 s15, s15, s28
	s_addc_u32 s29, s30, s29
	s_add_u32 s28, s34, s15
	v_mov_b32_e32 v39, v145
	s_addc_u32 s29, 0, s29
	v_lshlrev_b32_e32 v2, 1, v41
	v_lshlrev_b32_e32 v3, 3, v41
	v_lshl_add_u64 v[138:139], v[0:1], 0, v[38:39]
	v_lshl_add_u64 v[0:1], s[28:29], 0, v[32:33]
	v_mov_b32_e32 v137, 0
	s_waitcnt vmcnt(0)
	v_mov_b32_e32 v96, v218
	v_mov_b32_e32 v97, v219
	v_mov_b32_e32 v98, v220
	v_mov_b32_e32 v99, v221
	v_mov_b32_e32 v100, v222
	v_mov_b32_e32 v101, v223
	v_mov_b32_e32 v102, v224
	v_mov_b32_e32 v103, v225
	v_mov_b64_e32 v[106:107], v[102:103]
	v_mov_b64_e32 v[110:111], v[98:99]
	s_mov_b32 s39, s55
	s_mov_b32 s38, s54
	v_mul_u32_u24_e32 v154, 0x90, v40
	v_and_b32_e32 v155, 32, v2
	v_and_b32_e32 v157, 24, v3
	v_lshl_add_u64 v[140:141], v[34:35], 1, v[0:1]
	s_mov_b64 s[28:29], -1
	v_mov_b32_e32 v160, 0
	v_mov_b32_e32 v16, 0
	v_mov_b32_e32 v17, v137
	v_mov_b32_e32 v18, v137
	v_mov_b32_e32 v19, v137
	v_mov_b32_e32 v20, v137
	v_mov_b32_e32 v21, v137
	v_mov_b32_e32 v22, v137
	v_mov_b32_e32 v23, v137
	v_mov_b32_e32 v24, v137
	v_mov_b32_e32 v25, v137
	v_mov_b32_e32 v26, v137
	v_mov_b32_e32 v27, v137
	v_mov_b32_e32 v28, v137
	v_mov_b32_e32 v29, v137
	v_mov_b32_e32 v30, v137
	v_mov_b32_e32 v31, v137
	v_mov_b32_e32 v0, v137
	v_mov_b32_e32 v1, v137
	v_mov_b32_e32 v2, v137
	v_mov_b32_e32 v3, v137
	v_mov_b32_e32 v4, v137
	v_mov_b32_e32 v5, v137
	v_mov_b32_e32 v6, v137
	v_mov_b32_e32 v7, v137
	v_mov_b32_e32 v8, v137
	v_mov_b32_e32 v9, v137
	v_mov_b32_e32 v10, v137
	v_mov_b32_e32 v11, v137
	v_mov_b32_e32 v12, v137
	v_mov_b32_e32 v13, v137
	v_mov_b32_e32 v14, v137
	v_mov_b32_e32 v15, v137
	v_mov_b32_e32 v32, 0
	v_mov_b32_e32 v33, v137
	v_mov_b32_e32 v34, v137
	v_mov_b32_e32 v35, v137
	v_mov_b32_e32 v36, v137
	v_mov_b32_e32 v37, v137
	v_mov_b32_e32 v38, v137
	v_mov_b32_e32 v39, v137
	v_mov_b32_e32 v40, v137
	v_mov_b32_e32 v41, v137
	v_mov_b32_e32 v42, v137
	v_mov_b32_e32 v43, v137
	v_mov_b32_e32 v44, v137
	v_mov_b32_e32 v45, v137
	v_mov_b32_e32 v46, v137
	v_mov_b32_e32 v47, v137
	v_mov_b64_e32 v[104:105], v[100:101]
	v_mov_b64_e32 v[108:109], v[96:97]
	s_cmp_ge_u32 s68, s17
	s_cbranch_scc1 .LBB0_1272
